# wt_item loads de-serialized (3 sites) + gdn_prep counted vmcnt and grouped history loads
# speedup vs baseline: 1.0153x; 1.0153x over previous
.LBB0_35:
	s_ashr_i32 s29, s28, 31
	s_lshl_b32 s26, s26, 6
	v_add_u32_e32 v146, s28, v16
	s_lshl_b64 s[28:29], s[28:29], 2
	s_add_u32 s4, s4, s28
	v_cmp_gt_i32_e64 s[0:1], s38, v146
	s_addc_u32 s5, s5, s29
	v_lshl_add_u64 v[8:9], s[4:5], 0, v[18:19]
	s_ashr_i32 s27, s26, 31
	v_mov_b32_e32 v64, 0
	v_mov_b32_e32 v65, 0
	v_mov_b32_e32 v66, 0
	v_mov_b32_e32 v67, 0
	v_mov_b32_e32 v68, 0
	v_mov_b32_e32 v69, 0
	v_mov_b32_e32 v70, 0
	v_mov_b32_e32 v71, 0
	v_mov_b32_e32 v72, 0
	v_mov_b32_e32 v73, 0
	v_mov_b32_e32 v74, 0
	v_mov_b32_e32 v75, 0
	v_mov_b32_e32 v76, 0
	v_mov_b32_e32 v77, 0
	v_mov_b32_e32 v78, 0
	v_mov_b32_e32 v79, 0
	v_mov_b32_e32 v80, 0
	v_mov_b32_e32 v81, 0
	v_mov_b32_e32 v82, 0
	v_mov_b32_e32 v83, 0
	v_mov_b32_e32 v84, 0
	v_mov_b32_e32 v85, 0
	v_mov_b32_e32 v86, 0
	v_mov_b32_e32 v87, 0
	v_mov_b32_e32 v88, 0
	v_mov_b32_e32 v89, 0
	v_mov_b32_e32 v90, 0
	v_mov_b32_e32 v91, 0
	v_mov_b32_e32 v92, 0
	v_mov_b32_e32 v93, 0
	v_mov_b32_e32 v94, 0
	v_mov_b32_e32 v95, 0
	v_mov_b32_e32 v96, 0
	v_mov_b32_e32 v97, 0
	v_mov_b32_e32 v98, 0
	v_mov_b32_e32 v99, 0
	v_mov_b32_e32 v100, 0
	v_mov_b32_e32 v101, 0
	v_mov_b32_e32 v102, 0
	v_mov_b32_e32 v103, 0
	v_mov_b32_e32 v104, 0
	v_mov_b32_e32 v105, 0
	v_mov_b32_e32 v106, 0
	v_mov_b32_e32 v107, 0
	v_mov_b32_e32 v108, 0
	v_mov_b32_e32 v109, 0
	v_mov_b32_e32 v110, 0
	v_mov_b32_e32 v111, 0
	v_mov_b32_e32 v112, 0
	v_mov_b32_e32 v113, 0
	v_mov_b32_e32 v114, 0
	v_mov_b32_e32 v115, 0
	v_mov_b32_e32 v116, 0
	v_mov_b32_e32 v117, 0
	v_mov_b32_e32 v118, 0
	v_mov_b32_e32 v119, 0
	v_mov_b32_e32 v120, 0
	v_mov_b32_e32 v121, 0
	v_mov_b32_e32 v122, 0
	v_mov_b32_e32 v123, 0
	v_mov_b32_e32 v124, 0
	v_mov_b32_e32 v125, 0
	v_mov_b32_e32 v126, 0
	v_mov_b32_e32 v127, 0
	v_or_b32_e32 v146, s26, v14
	v_mul_lo_u32 v144, v146, s38
	v_mov_b32_e32 v145, 0
	v_lshl_add_u64 v[144:145], v[144:145], 2, v[8:9]
	s_lshl_b32 s40, s38, 4
	s_mov_b32 s41, 0
	s_and_saveexec_b64 s[30:31], s[0:1]
	s_cbranch_execz .Lwt1_noload
	global_load_dwordx4 v[64:67], v[144:145], off
	v_lshl_add_u64 v[144:145], v[144:145], 0, s[40:41]
	global_load_dwordx4 v[68:71], v[144:145], off
	v_lshl_add_u64 v[144:145], v[144:145], 0, s[40:41]
	global_load_dwordx4 v[72:75], v[144:145], off
	v_lshl_add_u64 v[144:145], v[144:145], 0, s[40:41]
	global_load_dwordx4 v[76:79], v[144:145], off
	v_lshl_add_u64 v[144:145], v[144:145], 0, s[40:41]
	global_load_dwordx4 v[80:83], v[144:145], off
	v_lshl_add_u64 v[144:145], v[144:145], 0, s[40:41]
	global_load_dwordx4 v[84:87], v[144:145], off
	v_lshl_add_u64 v[144:145], v[144:145], 0, s[40:41]
	global_load_dwordx4 v[88:91], v[144:145], off
	v_lshl_add_u64 v[144:145], v[144:145], 0, s[40:41]
	global_load_dwordx4 v[92:95], v[144:145], off
	v_lshl_add_u64 v[144:145], v[144:145], 0, s[40:41]
	global_load_dwordx4 v[96:99], v[144:145], off
	v_lshl_add_u64 v[144:145], v[144:145], 0, s[40:41]
	global_load_dwordx4 v[100:103], v[144:145], off
	v_lshl_add_u64 v[144:145], v[144:145], 0, s[40:41]
	global_load_dwordx4 v[104:107], v[144:145], off
	v_lshl_add_u64 v[144:145], v[144:145], 0, s[40:41]
	global_load_dwordx4 v[108:111], v[144:145], off
	v_lshl_add_u64 v[144:145], v[144:145], 0, s[40:41]
	global_load_dwordx4 v[112:115], v[144:145], off
	v_lshl_add_u64 v[144:145], v[144:145], 0, s[40:41]
	global_load_dwordx4 v[116:119], v[144:145], off
	v_lshl_add_u64 v[144:145], v[144:145], 0, s[40:41]
	global_load_dwordx4 v[120:123], v[144:145], off
	v_lshl_add_u64 v[144:145], v[144:145], 0, s[40:41]
	global_load_dwordx4 v[124:127], v[144:145], off
.Lwt1_noload:
	s_or_b64 exec, exec, s[30:31]
	s_cmp_eq_u64 s[24:25], 0
	s_cbranch_scc1 .Lwt1_noksc
	v_lshl_add_u64 v[148:149], s[26:27], 0, v[14:15]
	v_lshl_add_u64 v[148:149], v[148:149], 2, s[24:25]
	global_load_dword v128, v[148:149], off
	global_load_dword v129, v[148:149], off offset:16
	global_load_dword v130, v[148:149], off offset:32
	global_load_dword v131, v[148:149], off offset:48
	global_load_dword v132, v[148:149], off offset:64
	global_load_dword v133, v[148:149], off offset:80
	global_load_dword v134, v[148:149], off offset:96
	global_load_dword v135, v[148:149], off offset:112
	global_load_dword v136, v[148:149], off offset:128
	global_load_dword v137, v[148:149], off offset:144
	global_load_dword v138, v[148:149], off offset:160
	global_load_dword v139, v[148:149], off offset:176
	global_load_dword v140, v[148:149], off offset:192
	global_load_dword v141, v[148:149], off offset:208
	global_load_dword v142, v[148:149], off offset:224
	global_load_dword v143, v[148:149], off offset:240
	s_waitcnt vmcnt(0)
	v_mul_f32_e32 v64, v64, v128
	v_mul_f32_e32 v65, v65, v128
	v_mul_f32_e32 v66, v66, v128
	v_mul_f32_e32 v67, v67, v128
	v_mul_f32_e32 v68, v68, v129
	v_mul_f32_e32 v69, v69, v129
	v_mul_f32_e32 v70, v70, v129
	v_mul_f32_e32 v71, v71, v129
	v_mul_f32_e32 v72, v72, v130
	v_mul_f32_e32 v73, v73, v130
	v_mul_f32_e32 v74, v74, v130
	v_mul_f32_e32 v75, v75, v130
	v_mul_f32_e32 v76, v76, v131
	v_mul_f32_e32 v77, v77, v131
	v_mul_f32_e32 v78, v78, v131
	v_mul_f32_e32 v79, v79, v131
	v_mul_f32_e32 v80, v80, v132
	v_mul_f32_e32 v81, v81, v132
	v_mul_f32_e32 v82, v82, v132
	v_mul_f32_e32 v83, v83, v132
	v_mul_f32_e32 v84, v84, v133
	v_mul_f32_e32 v85, v85, v133
	v_mul_f32_e32 v86, v86, v133
	v_mul_f32_e32 v87, v87, v133
	v_mul_f32_e32 v88, v88, v134
	v_mul_f32_e32 v89, v89, v134
	v_mul_f32_e32 v90, v90, v134
	v_mul_f32_e32 v91, v91, v134
	v_mul_f32_e32 v92, v92, v135
	v_mul_f32_e32 v93, v93, v135
	v_mul_f32_e32 v94, v94, v135
	v_mul_f32_e32 v95, v95, v135
	v_mul_f32_e32 v96, v96, v136
	v_mul_f32_e32 v97, v97, v136
	v_mul_f32_e32 v98, v98, v136
	v_mul_f32_e32 v99, v99, v136
	v_mul_f32_e32 v100, v100, v137
	v_mul_f32_e32 v101, v101, v137
	v_mul_f32_e32 v102, v102, v137
	v_mul_f32_e32 v103, v103, v137
	v_mul_f32_e32 v104, v104, v138
	v_mul_f32_e32 v105, v105, v138
	v_mul_f32_e32 v106, v106, v138
	v_mul_f32_e32 v107, v107, v138
	v_mul_f32_e32 v108, v108, v139
	v_mul_f32_e32 v109, v109, v139
	v_mul_f32_e32 v110, v110, v139
	v_mul_f32_e32 v111, v111, v139
	v_mul_f32_e32 v112, v112, v140
	v_mul_f32_e32 v113, v113, v140
	v_mul_f32_e32 v114, v114, v140
	v_mul_f32_e32 v115, v115, v140
	v_mul_f32_e32 v116, v116, v141
	v_mul_f32_e32 v117, v117, v141
	v_mul_f32_e32 v118, v118, v141
	v_mul_f32_e32 v119, v119, v141
	v_mul_f32_e32 v120, v120, v142
	v_mul_f32_e32 v121, v121, v142
	v_mul_f32_e32 v122, v122, v142
	v_mul_f32_e32 v123, v123, v142
	v_mul_f32_e32 v124, v124, v143
	v_mul_f32_e32 v125, v125, v143
	v_mul_f32_e32 v126, v126, v143
	v_mul_f32_e32 v127, v127, v143
.Lwt1_noksc:
	s_waitcnt vmcnt(0)
	ds_write2_b32 v43, v64, v65 offset1:1
	ds_write2_b32 v43, v66, v67 offset0:2 offset1:3
	v_add_u32_e32 v146, 0x410, v43
	ds_write2_b32 v146, v68, v69 offset1:1
	ds_write2_b32 v146, v70, v71 offset0:2 offset1:3
	v_add_u32_e32 v146, 0x820, v43
	ds_write2_b32 v146, v72, v73 offset1:1
	ds_write2_b32 v146, v74, v75 offset0:2 offset1:3
	v_add_u32_e32 v146, 0xc30, v43
	ds_write2_b32 v146, v76, v77 offset1:1
	ds_write2_b32 v146, v78, v79 offset0:2 offset1:3
	v_add_u32_e32 v146, 0x1040, v43
	ds_write2_b32 v146, v80, v81 offset1:1
	ds_write2_b32 v146, v82, v83 offset0:2 offset1:3
	v_add_u32_e32 v146, 0x1450, v43
	ds_write2_b32 v146, v84, v85 offset1:1
	ds_write2_b32 v146, v86, v87 offset0:2 offset1:3
	v_add_u32_e32 v146, 0x1860, v43
	ds_write2_b32 v146, v88, v89 offset1:1
	ds_write2_b32 v146, v90, v91 offset0:2 offset1:3
	v_add_u32_e32 v146, 0x1c70, v43
	ds_write2_b32 v146, v92, v93 offset1:1
	ds_write2_b32 v146, v94, v95 offset0:2 offset1:3
	v_add_u32_e32 v146, 0x2080, v43
	ds_write2_b32 v146, v96, v97 offset1:1
	ds_write2_b32 v146, v98, v99 offset0:2 offset1:3
	v_add_u32_e32 v146, 0x2490, v43
	ds_write2_b32 v146, v100, v101 offset1:1
	ds_write2_b32 v146, v102, v103 offset0:2 offset1:3
	v_add_u32_e32 v146, 0x28a0, v43
	ds_write2_b32 v146, v104, v105 offset1:1
	ds_write2_b32 v146, v106, v107 offset0:2 offset1:3
	v_add_u32_e32 v146, 0x2cb0, v43
	ds_write2_b32 v146, v108, v109 offset1:1
	ds_write2_b32 v146, v110, v111 offset0:2 offset1:3
	v_add_u32_e32 v146, 0x30c0, v43
	ds_write2_b32 v146, v112, v113 offset1:1
	ds_write2_b32 v146, v114, v115 offset0:2 offset1:3
	v_add_u32_e32 v146, 0x34d0, v43
	ds_write2_b32 v146, v116, v117 offset1:1
	ds_write2_b32 v146, v118, v119 offset0:2 offset1:3
	v_add_u32_e32 v146, 0x38e0, v43
	ds_write2_b32 v146, v120, v121 offset1:1
	ds_write2_b32 v146, v122, v123 offset0:2 offset1:3
	v_mov_b32_e32 v8, v124
	v_mov_b32_e32 v9, v125
	v_mov_b32_e32 v10, v126
	v_mov_b32_e32 v11, v127
	s_branch .LBB0_13

.LBB0_342:
	s_ashr_i32 s21, s20, 31
	s_lshl_b32 s18, s18, 6
	v_add_u32_e32 v42, s20, v12
	s_lshl_b64 s[20:21], s[20:21], 2
	s_add_u32 s6, s6, s20
	v_cmp_gt_i32_e64 s[4:5], s26, v42
	s_addc_u32 s7, s7, s21
	v_lshlrev_b32_e32 v0, 2, v12
	v_lshl_add_u64 v[6:7], s[6:7], 0, v[0:1]
	s_ashr_i32 s19, s18, 31
	v_mov_b32_e32 v64, 0
	v_mov_b32_e32 v65, 0
	v_mov_b32_e32 v66, 0
	v_mov_b32_e32 v67, 0
	v_mov_b32_e32 v68, 0
	v_mov_b32_e32 v69, 0
	v_mov_b32_e32 v70, 0
	v_mov_b32_e32 v71, 0
	v_mov_b32_e32 v72, 0
	v_mov_b32_e32 v73, 0
	v_mov_b32_e32 v74, 0
	v_mov_b32_e32 v75, 0
	v_mov_b32_e32 v76, 0
	v_mov_b32_e32 v77, 0
	v_mov_b32_e32 v78, 0
	v_mov_b32_e32 v79, 0
	v_mov_b32_e32 v80, 0
	v_mov_b32_e32 v81, 0
	v_mov_b32_e32 v82, 0
	v_mov_b32_e32 v83, 0
	v_mov_b32_e32 v84, 0
	v_mov_b32_e32 v85, 0
	v_mov_b32_e32 v86, 0
	v_mov_b32_e32 v87, 0
	v_mov_b32_e32 v88, 0
	v_mov_b32_e32 v89, 0
	v_mov_b32_e32 v90, 0
	v_mov_b32_e32 v91, 0
	v_mov_b32_e32 v92, 0
	v_mov_b32_e32 v93, 0
	v_mov_b32_e32 v94, 0
	v_mov_b32_e32 v95, 0
	v_mov_b32_e32 v96, 0
	v_mov_b32_e32 v97, 0
	v_mov_b32_e32 v98, 0
	v_mov_b32_e32 v99, 0
	v_mov_b32_e32 v100, 0
	v_mov_b32_e32 v101, 0
	v_mov_b32_e32 v102, 0
	v_mov_b32_e32 v103, 0
	v_mov_b32_e32 v104, 0
	v_mov_b32_e32 v105, 0
	v_mov_b32_e32 v106, 0
	v_mov_b32_e32 v107, 0
	v_mov_b32_e32 v108, 0
	v_mov_b32_e32 v109, 0
	v_mov_b32_e32 v110, 0
	v_mov_b32_e32 v111, 0
	v_mov_b32_e32 v112, 0
	v_mov_b32_e32 v113, 0
	v_mov_b32_e32 v114, 0
	v_mov_b32_e32 v115, 0
	v_mov_b32_e32 v116, 0
	v_mov_b32_e32 v117, 0
	v_mov_b32_e32 v118, 0
	v_mov_b32_e32 v119, 0
	v_mov_b32_e32 v120, 0
	v_mov_b32_e32 v121, 0
	v_mov_b32_e32 v122, 0
	v_mov_b32_e32 v123, 0
	v_mov_b32_e32 v124, 0
	v_mov_b32_e32 v125, 0
	v_mov_b32_e32 v126, 0
	v_mov_b32_e32 v127, 0
	v_or_b32_e32 v42, s18, v10
	v_mul_lo_u32 v40, v42, s26
	v_mov_b32_e32 v41, 0
	v_lshl_add_u64 v[40:41], v[40:41], 2, v[6:7]
	s_lshl_b32 s28, s26, 4
	s_mov_b32 s29, 0
	s_and_saveexec_b64 s[22:23], s[4:5]
	s_cbranch_execz .Lwt2_noload
	global_load_dwordx4 v[64:67], v[40:41], off
	v_lshl_add_u64 v[40:41], v[40:41], 0, s[28:29]
	global_load_dwordx4 v[68:71], v[40:41], off
	v_lshl_add_u64 v[40:41], v[40:41], 0, s[28:29]
	global_load_dwordx4 v[72:75], v[40:41], off
	v_lshl_add_u64 v[40:41], v[40:41], 0, s[28:29]
	global_load_dwordx4 v[76:79], v[40:41], off
	v_lshl_add_u64 v[40:41], v[40:41], 0, s[28:29]
	global_load_dwordx4 v[80:83], v[40:41], off
	v_lshl_add_u64 v[40:41], v[40:41], 0, s[28:29]
	global_load_dwordx4 v[84:87], v[40:41], off
	v_lshl_add_u64 v[40:41], v[40:41], 0, s[28:29]
	global_load_dwordx4 v[88:91], v[40:41], off
	v_lshl_add_u64 v[40:41], v[40:41], 0, s[28:29]
	global_load_dwordx4 v[92:95], v[40:41], off
	v_lshl_add_u64 v[40:41], v[40:41], 0, s[28:29]
	global_load_dwordx4 v[96:99], v[40:41], off
	v_lshl_add_u64 v[40:41], v[40:41], 0, s[28:29]
	global_load_dwordx4 v[100:103], v[40:41], off
	v_lshl_add_u64 v[40:41], v[40:41], 0, s[28:29]
	global_load_dwordx4 v[104:107], v[40:41], off
	v_lshl_add_u64 v[40:41], v[40:41], 0, s[28:29]
	global_load_dwordx4 v[108:111], v[40:41], off
	v_lshl_add_u64 v[40:41], v[40:41], 0, s[28:29]
	global_load_dwordx4 v[112:115], v[40:41], off
	v_lshl_add_u64 v[40:41], v[40:41], 0, s[28:29]
	global_load_dwordx4 v[116:119], v[40:41], off
	v_lshl_add_u64 v[40:41], v[40:41], 0, s[28:29]
	global_load_dwordx4 v[120:123], v[40:41], off
	v_lshl_add_u64 v[40:41], v[40:41], 0, s[28:29]
	global_load_dwordx4 v[124:127], v[40:41], off
.Lwt2_noload:
	s_or_b64 exec, exec, s[22:23]
	s_cmp_eq_u64 s[10:11], 0
	s_cbranch_scc1 .Lwt2_noksc
	v_lshl_add_u64 v[44:45], s[18:19], 0, v[10:11]
	v_lshl_add_u64 v[44:45], v[44:45], 2, s[10:11]
	global_load_dword v48, v[44:45], off
	global_load_dword v49, v[44:45], off offset:16
	global_load_dword v50, v[44:45], off offset:32
	global_load_dword v51, v[44:45], off offset:48
	global_load_dword v52, v[44:45], off offset:64
	global_load_dword v53, v[44:45], off offset:80
	global_load_dword v54, v[44:45], off offset:96
	global_load_dword v55, v[44:45], off offset:112
	global_load_dword v56, v[44:45], off offset:128
	global_load_dword v57, v[44:45], off offset:144
	global_load_dword v58, v[44:45], off offset:160
	global_load_dword v59, v[44:45], off offset:176
	global_load_dword v60, v[44:45], off offset:192
	global_load_dword v61, v[44:45], off offset:208
	global_load_dword v62, v[44:45], off offset:224
	global_load_dword v63, v[44:45], off offset:240
	s_waitcnt vmcnt(0)
	v_mul_f32_e32 v64, v64, v48
	v_mul_f32_e32 v65, v65, v48
	v_mul_f32_e32 v66, v66, v48
	v_mul_f32_e32 v67, v67, v48
	v_mul_f32_e32 v68, v68, v49
	v_mul_f32_e32 v69, v69, v49
	v_mul_f32_e32 v70, v70, v49
	v_mul_f32_e32 v71, v71, v49
	v_mul_f32_e32 v72, v72, v50
	v_mul_f32_e32 v73, v73, v50
	v_mul_f32_e32 v74, v74, v50
	v_mul_f32_e32 v75, v75, v50
	v_mul_f32_e32 v76, v76, v51
	v_mul_f32_e32 v77, v77, v51
	v_mul_f32_e32 v78, v78, v51
	v_mul_f32_e32 v79, v79, v51
	v_mul_f32_e32 v80, v80, v52
	v_mul_f32_e32 v81, v81, v52
	v_mul_f32_e32 v82, v82, v52
	v_mul_f32_e32 v83, v83, v52
	v_mul_f32_e32 v84, v84, v53
	v_mul_f32_e32 v85, v85, v53
	v_mul_f32_e32 v86, v86, v53
	v_mul_f32_e32 v87, v87, v53
	v_mul_f32_e32 v88, v88, v54
	v_mul_f32_e32 v89, v89, v54
	v_mul_f32_e32 v90, v90, v54
	v_mul_f32_e32 v91, v91, v54
	v_mul_f32_e32 v92, v92, v55
	v_mul_f32_e32 v93, v93, v55
	v_mul_f32_e32 v94, v94, v55
	v_mul_f32_e32 v95, v95, v55
	v_mul_f32_e32 v96, v96, v56
	v_mul_f32_e32 v97, v97, v56
	v_mul_f32_e32 v98, v98, v56
	v_mul_f32_e32 v99, v99, v56
	v_mul_f32_e32 v100, v100, v57
	v_mul_f32_e32 v101, v101, v57
	v_mul_f32_e32 v102, v102, v57
	v_mul_f32_e32 v103, v103, v57
	v_mul_f32_e32 v104, v104, v58
	v_mul_f32_e32 v105, v105, v58
	v_mul_f32_e32 v106, v106, v58
	v_mul_f32_e32 v107, v107, v58
	v_mul_f32_e32 v108, v108, v59
	v_mul_f32_e32 v109, v109, v59
	v_mul_f32_e32 v110, v110, v59
	v_mul_f32_e32 v111, v111, v59
	v_mul_f32_e32 v112, v112, v60
	v_mul_f32_e32 v113, v113, v60
	v_mul_f32_e32 v114, v114, v60
	v_mul_f32_e32 v115, v115, v60
	v_mul_f32_e32 v116, v116, v61
	v_mul_f32_e32 v117, v117, v61
	v_mul_f32_e32 v118, v118, v61
	v_mul_f32_e32 v119, v119, v61
	v_mul_f32_e32 v120, v120, v62
	v_mul_f32_e32 v121, v121, v62
	v_mul_f32_e32 v122, v122, v62
	v_mul_f32_e32 v123, v123, v62
	v_mul_f32_e32 v124, v124, v63
	v_mul_f32_e32 v125, v125, v63
	v_mul_f32_e32 v126, v126, v63
	v_mul_f32_e32 v127, v127, v63
.Lwt2_noksc:
	s_waitcnt vmcnt(0)
	ds_write2_b32 v39, v64, v65 offset1:1
	ds_write2_b32 v39, v66, v67 offset0:2 offset1:3
	v_add_u32_e32 v42, 0x410, v39
	ds_write2_b32 v42, v68, v69 offset1:1
	ds_write2_b32 v42, v70, v71 offset0:2 offset1:3
	v_add_u32_e32 v42, 0x820, v39
	ds_write2_b32 v42, v72, v73 offset1:1
	ds_write2_b32 v42, v74, v75 offset0:2 offset1:3
	v_add_u32_e32 v42, 0xc30, v39
	ds_write2_b32 v42, v76, v77 offset1:1
	ds_write2_b32 v42, v78, v79 offset0:2 offset1:3
	v_add_u32_e32 v42, 0x1040, v39
	ds_write2_b32 v42, v80, v81 offset1:1
	ds_write2_b32 v42, v82, v83 offset0:2 offset1:3
	v_add_u32_e32 v42, 0x1450, v39
	ds_write2_b32 v42, v84, v85 offset1:1
	ds_write2_b32 v42, v86, v87 offset0:2 offset1:3
	v_add_u32_e32 v42, 0x1860, v39
	ds_write2_b32 v42, v88, v89 offset1:1
	ds_write2_b32 v42, v90, v91 offset0:2 offset1:3
	v_add_u32_e32 v42, 0x1c70, v39
	ds_write2_b32 v42, v92, v93 offset1:1
	ds_write2_b32 v42, v94, v95 offset0:2 offset1:3
	v_add_u32_e32 v42, 0x2080, v39
	ds_write2_b32 v42, v96, v97 offset1:1
	ds_write2_b32 v42, v98, v99 offset0:2 offset1:3
	v_add_u32_e32 v42, 0x2490, v39
	ds_write2_b32 v42, v100, v101 offset1:1
	ds_write2_b32 v42, v102, v103 offset0:2 offset1:3
	v_add_u32_e32 v42, 0x28a0, v39
	ds_write2_b32 v42, v104, v105 offset1:1
	ds_write2_b32 v42, v106, v107 offset0:2 offset1:3
	v_add_u32_e32 v42, 0x2cb0, v39
	ds_write2_b32 v42, v108, v109 offset1:1
	ds_write2_b32 v42, v110, v111 offset0:2 offset1:3
	v_add_u32_e32 v42, 0x30c0, v39
	ds_write2_b32 v42, v112, v113 offset1:1
	ds_write2_b32 v42, v114, v115 offset0:2 offset1:3
	v_add_u32_e32 v42, 0x34d0, v39
	ds_write2_b32 v42, v116, v117 offset1:1
	ds_write2_b32 v42, v118, v119 offset0:2 offset1:3
	v_add_u32_e32 v42, 0x38e0, v39
	ds_write2_b32 v42, v120, v121 offset1:1
	ds_write2_b32 v42, v122, v123 offset0:2 offset1:3
	v_mov_b32_e32 v6, v124
	v_mov_b32_e32 v7, v125
	v_mov_b32_e32 v8, v126
	v_mov_b32_e32 v9, v127
	s_branch .LBB0_321

.LBB0_556:
	v_ashrrev_i32_e32 v102, 5, v117
	v_lshlrev_b32_e32 v32, 7, v102
	s_movk_i32 s12, 0x180
	v_and_or_b32 v106, v32, s12, v118
	v_readlane_b32 s36, v254, 12
	v_lshlrev_b32_e32 v98, 2, v106
	v_readlane_b32 s42, v254, 18
	v_readlane_b32 s43, v254, 19
	s_mov_b64 s[12:13], 0x1800
	s_nop 3
	global_load_dwordx4 v[32:35], v98, s[42:43] offset:16
	global_load_dwordx4 v[36:39], v98, s[42:43]
	v_lshl_add_u64 v[56:57], s[42:43], 0, v[98:99]
	v_lshl_add_u64 v[44:45], v[56:57], 0, s[12:13]
	v_add_co_u32_e32 v40, vcc, s15, v56
	s_mov_b64 s[12:13], 0x3000
	s_nop 0
	v_addc_co_u32_e32 v41, vcc, 0, v57, vcc
	v_lshl_add_u64 v[52:53], v[56:57], 0, s[12:13]
	s_movk_i32 s12, 0x3000
	v_add_co_u32_e32 v48, vcc, s12, v56
	s_mov_b64 s[12:13], 0x4800
	s_nop 0
	v_addc_co_u32_e32 v49, vcc, 0, v57, vcc
	v_lshl_add_u64 v[60:61], v[56:57], 0, s[12:13]
	v_add_co_u32_e32 v56, vcc, s16, v56
	global_load_dwordx4 v[40:43], v[40:41], off offset:2048
	s_nop 0
	global_load_dwordx4 v[44:47], v[44:45], off offset:16
	v_addc_co_u32_e32 v57, vcc, 0, v57, vcc
	global_load_dwordx4 v[48:51], v[48:49], off
	s_nop 0
	global_load_dwordx4 v[52:55], v[52:53], off offset:16
	s_nop 0
	global_load_dwordx4 v[56:59], v[56:57], off offset:2048
	s_nop 0
	global_load_dwordx4 v[60:63], v[60:61], off offset:16
	v_ashrrev_i32_e32 v104, 7, v117
	v_lshlrev_b32_e32 v64, 6, v117
	v_ashrrev_i32_e32 v105, 31, v104
	v_and_b32_e32 v68, 0x7c0, v64
	v_lshlrev_b64 v[64:65], 11, v[104:105]
	v_or_b32_e32 v64, v64, v68
	v_mad_u64_u32 v[66:67], s[12:13], v64, s17, v[100:101]
	v_mad_i32_i24 v67, v65, s17, v67
	v_lshlrev_b32_e32 v98, 1, v106
	v_lshl_add_u64 v[64:65], v[66:67], 0, v[98:99]
	s_mov_b64 s[12:13], 0x2000480
	v_mov_b32_e32 v98, v99
	v_lshl_add_u64 v[64:65], v[64:65], 0, s[12:13]
	v_cmp_ne_u32_e32 vcc, 0, v68
	v_mov_b64_e32 v[114:115], v[98:99]
	v_mov_b64_e32 v[110:111], v[98:99]
	v_mov_b64_e32 v[108:109], v[98:99]
	v_mov_b64_e32 v[112:113], v[98:99]
	v_mov_b32_e32 v133, 0
	v_mov_b32_e32 v130, 0
	v_mov_b32_e32 v132, 0
	v_mov_b32_e32 v128, 0
	v_mov_b32_e32 v134, 0
	v_mov_b32_e32 v129, 0
	v_mov_b32_e32 v135, 0
	v_mov_b32_e32 v131, 0
	v_mov_b32_e32 v125, 0
	v_mov_b32_e32 v122, 0
	v_mov_b32_e32 v124, 0
	v_mov_b32_e32 v120, 0
	v_mov_b32_e32 v126, 0
	v_mov_b32_e32 v121, 0
	v_mov_b32_e32 v127, 0
	v_mov_b32_e32 v123, 0
	v_readlane_b32 s37, v254, 13
	v_readlane_b32 s38, v254, 14
	v_readlane_b32 s39, v254, 15
	v_readlane_b32 s40, v254, 16
	v_readlane_b32 s41, v254, 17
	v_readlane_b32 s44, v254, 20
	v_readlane_b32 s45, v254, 21
	v_readlane_b32 s46, v254, 22
	v_readlane_b32 s47, v254, 23
	v_readlane_b32 s48, v254, 24
	v_readlane_b32 s49, v254, 25
	v_readlane_b32 s50, v254, 26
	v_readlane_b32 s51, v254, 27
	s_and_saveexec_b64 s[12:13], vcc
	s_cbranch_execz .LBB0_558
	v_add_co_u32_e32 v66, vcc, 0xffffc000, v64
	s_movk_i32 s18, 0xe000
	s_nop 0
	v_addc_co_u32_e32 v67, vcc, -1, v65, vcc
	global_load_dwordx4 v[66:69], v[66:67], off offset:-512
	v_add_co_u32_e32 v0, vcc, s18, v64
	s_nop 1
	v_addc_co_u32_e32 v1, vcc, -1, v65, vcc
	global_load_dwordx4 v[0:3], v[0:1], off offset:-3072
	v_add_co_u32_e32 v4, vcc, 0xfffff000, v64
	s_nop 1
	v_addc_co_u32_e32 v5, vcc, -1, v65, vcc
	global_load_dwordx4 v[4:7], v[4:5], off offset:-1536
	s_waitcnt vmcnt(0)
	v_and_b32_e32 v113, 0xffff0000, v66
	v_lshlrev_b32_e32 v112, 16, v66
	v_and_b32_e32 v109, 0xffff0000, v67
	v_lshlrev_b32_e32 v108, 16, v67
	v_and_b32_e32 v111, 0xffff0000, v68
	v_lshlrev_b32_e32 v110, 16, v68
	v_and_b32_e32 v115, 0xffff0000, v69
	v_lshlrev_b32_e32 v114, 16, v69
	v_and_b32_e32 v122, 0xffff0000, v0
	v_lshlrev_b32_e32 v125, 16, v0
	v_and_b32_e32 v120, 0xffff0000, v1
	v_lshlrev_b32_e32 v124, 16, v1
	v_and_b32_e32 v121, 0xffff0000, v2
	v_and_b32_e32 v123, 0xffff0000, v3
	v_lshlrev_b32_e32 v126, 16, v2
	v_lshlrev_b32_e32 v127, 16, v3
	v_and_b32_e32 v130, 0xffff0000, v4
	v_and_b32_e32 v128, 0xffff0000, v5
	v_and_b32_e32 v129, 0xffff0000, v6
	v_and_b32_e32 v131, 0xffff0000, v7
	v_lshlrev_b32_e32 v133, 16, v4
	v_lshlrev_b32_e32 v132, 16, v5
	v_lshlrev_b32_e32 v134, 16, v6
	v_lshlrev_b32_e32 v135, 16, v7

.LBB0_560:
	s_cmp_eq_u32 s18, 8
	s_cbranch_scc1 .Lgdn_first
	s_waitcnt vmcnt(16)
	s_branch .Lgdn_body
.Lgdn_first:
	s_waitcnt vmcnt(8)
.Lgdn_body:
	v_lshlrev_b32_e32 v136, 16, v95
	v_and_b32_e32 v98, 0xffff0000, v95
	v_mul_f32_e32 v95, v42, v124
	v_fmac_f32_e32 v95, v38, v108
	v_lshlrev_b32_e32 v140, 16, v93
	v_fmac_f32_e32 v95, v50, v132
	v_fmac_f32_e32 v95, v58, v140
	v_mul_f32_e32 v106, 0xbfb8aa3b, v95
	v_exp_f32_e32 v106, v106
	v_and_b32_e32 v139, 0xffff0000, v93
	v_lshlrev_b32_e32 v138, 16, v94
	v_and_b32_e32 v137, 0xffff0000, v94
	v_add_f32_e32 v106, 1.0, v106
	v_rcp_f32_e32 v106, v106
	v_lshlrev_b32_e32 v142, 16, v92
	v_and_b32_e32 v141, 0xffff0000, v92
	v_mul_f32_e32 v92, v40, v125
	v_mul_f32_e32 v95, v95, v106
	v_mul_f32_e32 v106, v43, v120
	v_fmac_f32_e32 v106, v39, v109
	v_fmac_f32_e32 v106, v51, v128
	v_fmac_f32_e32 v106, v59, v139
	v_mul_f32_e32 v107, 0xbfb8aa3b, v106
	v_exp_f32_e32 v107, v107
	v_fmac_f32_e32 v92, v36, v112
	v_fmac_f32_e32 v92, v48, v133
	v_fmac_f32_e32 v92, v56, v142
	v_add_f32_e32 v107, 1.0, v107
	v_rcp_f32_e32 v107, v107
	v_mul_f32_e32 v93, 0xbfb8aa3b, v92
	v_exp_f32_e32 v93, v93
	v_mul_f32_e32 v106, v106, v107
	v_mul_f32_e32 v107, v44, v126
	v_fmac_f32_e32 v107, v32, v110
	v_fmac_f32_e32 v107, v52, v134
	v_fmac_f32_e32 v107, v60, v138
	v_mul_f32_e32 v108, 0xbfb8aa3b, v107
	v_exp_f32_e32 v108, v108
	v_add_f32_e32 v93, 1.0, v93
	v_rcp_f32_e32 v93, v93
	v_add_f32_e32 v108, 1.0, v108
	v_rcp_f32_e32 v108, v108
	v_mul_f32_e32 v92, v92, v93
	v_mul_f32_e32 v93, v41, v122
	v_fmac_f32_e32 v93, v37, v113
	v_mul_f32_e32 v107, v107, v108
	v_mul_f32_e32 v108, v45, v121
	v_fmac_f32_e32 v108, v33, v111
	v_fmac_f32_e32 v108, v53, v129
	v_fmac_f32_e32 v108, v61, v137
	v_mul_f32_e32 v109, 0xbfb8aa3b, v108
	v_exp_f32_e32 v109, v109
	v_fmac_f32_e32 v93, v49, v130
	v_fmac_f32_e32 v93, v57, v141
	v_mul_f32_e32 v94, 0xbfb8aa3b, v93
	v_add_f32_e32 v109, 1.0, v109
	v_rcp_f32_e32 v109, v109
	v_exp_f32_e32 v94, v94
	v_mul_f32_e32 v108, v108, v109
	v_mul_f32_e32 v109, v46, v127
	v_fmac_f32_e32 v109, v34, v114
	v_fmac_f32_e32 v109, v54, v135
	v_fmac_f32_e32 v109, v62, v136
	v_mul_f32_e32 v110, 0xbfb8aa3b, v109
	v_exp_f32_e32 v110, v110
	v_add_f32_e32 v94, 1.0, v94
	v_rcp_f32_e32 v94, v94
	v_add_f32_e32 v110, 1.0, v110
	v_rcp_f32_e32 v110, v110
	v_mul_f32_e32 v93, v93, v94
	v_mul_f32_e32 v94, v93, v93
	v_fmac_f32_e32 v94, v92, v92
	v_mul_f32_e32 v109, v109, v110
	v_mul_f32_e32 v110, v47, v123
	v_fmac_f32_e32 v110, v35, v115
	v_fmac_f32_e32 v110, v55, v131
	v_fmac_f32_e32 v110, v63, v98
	v_mul_f32_e32 v111, 0xbfb8aa3b, v110
	v_exp_f32_e32 v111, v111
	v_fmac_f32_e32 v94, v95, v95
	v_fmac_f32_e32 v94, v106, v106
	v_fmac_f32_e32 v94, v107, v107
	v_add_f32_e32 v111, 1.0, v111
	v_rcp_f32_e32 v111, v111
	v_fmac_f32_e32 v94, v108, v108
	v_fmac_f32_e32 v94, v109, v109
	v_mul_f32_e32 v110, v110, v111
	v_fmac_f32_e32 v94, v110, v110
	s_nop 1
	v_add_f32_dpp v94, v94, v94 quad_perm:[1,0,3,2] row_mask:0xf bank_mask:0xf bound_ctrl:1
	s_nop 1
	v_add_f32_dpp v94, v94, v94 quad_perm:[2,3,0,1] row_mask:0xf bank_mask:0xf bound_ctrl:1
	s_nop 1
	v_add_f32_dpp v94, v94, v94 row_half_mirror row_mask:0xf bank_mask:0xf bound_ctrl:1
	s_nop 1
	v_add_f32_dpp v94, v94, v94 row_mirror row_mask:0xf bank_mask:0xf bound_ctrl:1
	v_add_f32_e32 v94, 0x358637bd, v94
	v_rsq_f32_e32 v94, v94
	s_nop 0
	v_mul_f32_e32 v111, 0x3db504f3, v94
	v_cndmask_b32_e64 v94, 1.0, v94, s[6:7]
	v_cndmask_b32_e64 v111, v94, v111, s[8:9]
	v_mul_f32_e32 v92, v92, v111
	v_mul_f32_e32 v93, v93, v111
	v_cvt_pk_bf16_f32 v92, v92, v93
	v_mul_f32_e32 v93, v95, v111
	v_mul_f32_e32 v94, v106, v111
	v_cvt_pk_bf16_f32 v93, v93, v94
	v_mul_f32_e32 v94, v107, v111
	v_mul_f32_e32 v95, v108, v111
	v_cvt_pk_bf16_f32 v94, v94, v95
	v_mul_f32_e32 v95, v109, v111
	v_mul_f32_e32 v106, v110, v111
	v_cvt_pk_bf16_f32 v95, v95, v106
	v_lshl_add_u64 v[106:107], s[92:93], 0, v[104:105]
	s_and_saveexec_b64 s[12:13], s[4:5]
	s_cbranch_execz .LBB0_562
	global_store_dwordx4 v[106:107], v[92:95], off

.LBB0_576:
	s_or_b64 exec, exec, s[12:13]
	s_mov_b64 s[12:13], 0xb000
	v_lshl_add_u64 v[102:103], v[102:103], 0, s[12:13]
	s_add_i32 s18, s18, -1
	s_mov_b64 s[12:13], 0x800
	s_cmp_eq_u32 s18, 0
	v_lshl_add_u64 v[104:105], v[104:105], 0, s[12:13]
	s_cbranch_scc1 .LBB0_555
	s_waitcnt vmcnt(8)
	v_mov_b64_e32 v[66:67], v[30:31]
	v_mov_b64_e32 v[70:71], v[26:27]
	v_mov_b64_e32 v[74:75], v[22:23]
	v_mov_b64_e32 v[78:79], v[18:19]
	v_mov_b64_e32 v[82:83], v[14:15]
	v_mov_b64_e32 v[86:87], v[10:11]
	v_mov_b64_e32 v[90:91], v[6:7]
	v_mov_b64_e32 v[94:95], v[2:3]
	v_mov_b64_e32 v[64:65], v[28:29]
	v_mov_b64_e32 v[68:69], v[24:25]
	v_mov_b64_e32 v[72:73], v[20:21]
	v_mov_b64_e32 v[76:77], v[16:17]
	v_mov_b64_e32 v[80:81], v[12:13]
	v_mov_b64_e32 v[84:85], v[8:9]
	v_mov_b64_e32 v[88:89], v[4:5]
	v_mov_b64_e32 v[92:93], v[0:1]
	s_cmp_eq_u32 s18, 1
	s_cbranch_scc0 .LBB0_559
	s_branch .LBB0_560
